# combined: v19 + attention PV V-read hoist + LRU-B conv lone-read hoist + dead RNE leftovers removed
# speedup vs baseline: 1.0064x; 1.0014x over previous
; #define LAS __attribute__((address_space(3)))
; __device__ __forceinline__ unsigned pk2(float lo, float hi) { return f2bf(lo) | (f2bf(hi) << 16); }
; #define MFMA16(a, b, c) __builtin_amdgcn_mfma_f32_16x16x32_bf16(a, b, c, 0, 0, 0)
; __device__ __forceinline__ v4i16_t vtr(const LAS unsigned char* p) { return __builtin_amdgcn_ds_read_tr16_b64_v4i16((LAS v4i16_t*)p); }
; __device__ __forceinline__ void attn_phase(const Params& p, LAS unsigned char* lds, const int bx, const int G, const int tid) {
;     ...
;         const int qi = 16 * wq + fr; float mx = -3e38f;
; #pragma unroll
;         for (int j = 0; j < 9; ++j)
; #pragma unroll
;             for (int e = 0; e < 4; ++e) { const int u = 16 * (wq + j) + 4 * fq + e, jk = X.nb * 64 - 64 + u, dl = u - 64 - qi; const bool ok = jk >= 0 && jk < X.n && dl >= -64 && dl <= 64;
;                 const float b = ((const LAS float*)(L + AT_BIAS))[ok ? dl + 64 : 0]; const float sv = ok ? st[j][e] + b : -1e30f; st[j][e] = sv; mx = fmaxf(mx, sv); }
;         mx = fmaxf(mx, __shfl_xor(mx, 16)); mx = fmaxf(mx, __shfl_xor(mx, 32));
;         float sm = 0.f;
; #pragma unroll
;         for (int j = 0; j < 9; ++j)
; #pragma unroll
;             for (int e = 0; e < 4; ++e) { const float pv = __expf(st[j][e] - mx); st[j][e] = pv; sm += pv; }
;         sm += __shfl_xor(sm, 16); sm += __shfl_xor(sm, 32);
;         f32x4 ot[4];
; #pragma unroll
;         for (int dt = 0; dt < 4; ++dt) ot[dt] = (f32x4){0.f, 0.f, 0.f, 0.f};
; #pragma unroll
;         for (int ks = 0; ks < 5; ++ks) { v4u pw; pw.x = pk2(st[2 * ks][0], st[2 * ks][1]); pw.y = pk2(st[2 * ks][2], st[2 * ks][3]); pw.z = pk2(st[2 * ks + 1][0], st[2 * ks + 1][1]); pw.w = pk2(st[2 * ks + 1][2], st[2 * ks + 1][3]);
;             const bf16x8 pb = __builtin_bit_cast(bf16x8, pw);
; #pragma unroll
;             for (int dt = 0; dt < 4; ++dt) { const LAS unsigned char* vr = vbp + ks * 5120 + dt * 32;
;                 const v4i16_t lo = vtr(vr), hi = vtr(vr + 16 * 160);
;                 ot[dt] = MFMA16(__builtin_shufflevector(lo, hi, 0, 1, 2, 3, 4, 5, 6, 7), pb, ot[dt]); } }
.LBB0_487:
	s_or_b64 exec, exec, s[12:13]
	s_mov_b32 s2, 0xff61b1e6
	v_max3_f32 v60, v66, s2, v65
	v_max3_f32 v60, v60, v96, v67
	v_max3_f32 v60, v60, v98, v97
	v_max3_f32 v60, v60, v93, v92
	v_max3_f32 v60, v60, v95, v94
	v_max3_f32 v60, v60, v89, v88
	v_max3_f32 v60, v60, v91, v90
	v_max3_f32 v60, v60, v85, v84
	v_max3_f32 v60, v60, v87, v86
	v_max3_f32 v60, v60, v99, v80
	v_max3_f32 v60, v60, v82, v81
	v_max3_f32 v60, v60, v83, v76
	v_max3_f32 v60, v60, v188, v187
	v_max3_f32 v60, v60, v73, v72
	v_max3_f32 v60, v60, v75, v74
	v_max3_f32 v60, v60, v190, v68
	v_max3_f32 v60, v60, v192, v191
	v_max3_f32 v60, v60, v195, v194
	ds_bpermute_b32 v62, v122, v60
	s_lshl_b32 s12, s37, 6
	s_add_i32 s13, s12, 0x7fffc000
	s_and_b32 s13, s13, 0x7ffff800
	s_and_b32 s50, s56, s86
	s_waitcnt lgkmcnt(0)
	v_max_f32_e32 v62, v62, v62
	v_max_f32_e32 v60, v60, v62
	ds_bpermute_b32 v62, v123, v60
	s_add_i32 s37, s13, 0x4000
	s_and_b32 s51, s12, 0x2000
	s_and_b64 s[12:13], s[40:41], exec
	s_cselect_b32 s13, 7, 5
	s_waitcnt lgkmcnt(0)
	v_max_f32_e32 v62, v62, v62
	v_max_f32_e32 v60, v60, v62
	v_sub_f32_e32 v63, v65, v60
	v_mul_f32_e32 v63, 0x3fb8aa3b, v63
	v_exp_f32_e32 v107, v63
	v_sub_f32_e32 v63, v96, v60
	v_mul_f32_e32 v63, 0x3fb8aa3b, v63
	v_exp_f32_e32 v96, v63
	v_sub_f32_e32 v63, v67, v60
	v_mul_f32_e32 v63, 0x3fb8aa3b, v63
	v_exp_f32_e32 v150, v63
	v_sub_f32_e32 v63, v98, v60
	v_mul_f32_e32 v63, 0x3fb8aa3b, v63
	v_exp_f32_e32 v98, v63
	v_sub_f32_e32 v63, v97, v60
	v_mul_f32_e32 v63, 0x3fb8aa3b, v63
	v_exp_f32_e32 v97, v63
	v_sub_f32_e32 v63, v93, v60
	v_mul_f32_e32 v63, 0x3fb8aa3b, v63
	v_exp_f32_e32 v151, v63
	v_sub_f32_e32 v63, v92, v60
	v_mul_f32_e32 v63, 0x3fb8aa3b, v63
	v_exp_f32_e32 v152, v63
	v_sub_f32_e32 v63, v95, v60
	v_mul_f32_e32 v63, 0x3fb8aa3b, v63
	v_exp_f32_e32 v92, v63
	v_sub_f32_e32 v63, v94, v60
	v_mul_f32_e32 v63, 0x3fb8aa3b, v63
	v_exp_f32_e32 v93, v63
	v_sub_f32_e32 v63, v89, v60
	v_sub_f32_e32 v62, v66, v60
	v_mul_f32_e32 v63, 0x3fb8aa3b, v63
	v_mul_f32_e32 v62, 0x3fb8aa3b, v62
	v_exp_f32_e32 v89, v63
	v_sub_f32_e32 v63, v88, v60
	v_exp_f32_e32 v105, v62
	v_mul_f32_e32 v63, 0x3fb8aa3b, v63
	v_exp_f32_e32 v88, v63
	v_sub_f32_e32 v63, v91, v60
	v_mul_f32_e32 v63, 0x3fb8aa3b, v63
	v_exp_f32_e32 v91, v63
	v_sub_f32_e32 v63, v90, v60
	v_add_f32_e32 v62, 0, v105
	v_mul_f32_e32 v63, 0x3fb8aa3b, v63
	v_add_f32_e32 v62, v107, v62
	v_exp_f32_e32 v90, v63
	v_sub_f32_e32 v63, v85, v60
	v_add_f32_e32 v62, v96, v62
	v_mul_f32_e32 v63, 0x3fb8aa3b, v63
	v_add_f32_e32 v62, v150, v62
	v_exp_f32_e32 v85, v63
	v_sub_f32_e32 v63, v84, v60
	v_add_f32_e32 v62, v98, v62
	v_mul_f32_e32 v63, 0x3fb8aa3b, v63
	v_add_f32_e32 v62, v97, v62
	v_exp_f32_e32 v196, v63
	v_sub_f32_e32 v63, v87, v60
	v_add_f32_e32 v62, v151, v62
	v_mul_f32_e32 v63, 0x3fb8aa3b, v63
	v_add_f32_e32 v62, v152, v62
	v_exp_f32_e32 v77, v63
	v_sub_f32_e32 v63, v86, v60
	v_add_f32_e32 v62, v92, v62
	v_mul_f32_e32 v63, 0x3fb8aa3b, v63
	v_bfe_u32 v87, v97, 16, 1
	v_bfe_u32 v95, v107, 16, 1
	v_add_f32_e32 v62, v93, v62
	v_exp_f32_e32 v79, v63
	v_sub_f32_e32 v63, v99, v60
	v_add3_u32 v99, v107, v95, s33
	v_add3_u32 v87, v97, v87, s33
	v_bfe_u32 v95, v105, 16, 1
	v_bfe_u32 v97, v96, 16, 1
	v_bfe_u32 v107, v98, 16, 1
	v_add_f32_e32 v62, v89, v62
	v_bfe_u32 v94, v150, 16, 1
	v_add3_u32 v98, v98, v107, s33
	v_add3_u32 v96, v96, v97, s33
	v_add3_u32 v95, v105, v95, s33
	v_add_f32_e32 v62, v88, v62
	v_add3_u32 v94, v150, v94, s33
	v_bfe_u32 v150, v151, 16, 1
	v_lshrrev_b32_e32 v105, 16, v95
	v_lshrrev_b32_e32 v95, 16, v96
	v_lshrrev_b32_e32 v96, 16, v98
	v_add_f32_e32 v62, v91, v62
	v_bfe_u32 v86, v152, 16, 1
	v_add3_u32 v150, v151, v150, s33
	v_and_or_b32 v96, v87, s11, v96
	v_and_or_b32 v95, v94, s11, v95
	v_and_or_b32 v94, v99, s11, v105
	v_bfe_u32 v87, v90, 16, 1
	v_bfe_u32 v98, v88, 16, 1
	v_bfe_u32 v99, v93, 16, 1
	v_add_f32_e32 v62, v90, v62
	v_add3_u32 v86, v152, v86, s33
	v_lshrrev_b32_e32 v97, 16, v150
	ds_read_b64_tr_b16 v[152:153], v186 offset:30208
	ds_read_b64_tr_b16 v[150:151], v186 offset:27648
	ds_read_b64_tr_b16 v[198:199], v186 offset:27680
	ds_read_b64_tr_b16 v[200:201], v186 offset:30240
	v_add3_u32 v93, v93, v99, s33
	v_add3_u32 v98, v88, v98, s33
	v_add3_u32 v87, v90, v87, s33
	v_bfe_u32 v88, v92, 16, 1
	v_bfe_u32 v90, v89, 16, 1
	v_bfe_u32 v99, v91, 16, 1
	v_bfe_u32 v105, v85, 16, 1
	v_add_f32_e32 v62, v85, v62
	v_and_or_b32 v97, v86, s11, v97
	v_add3_u32 v91, v91, v99, s33
	v_add3_u32 v89, v89, v90, s33
	v_add3_u32 v88, v92, v88, s33
	v_lshrrev_b32_e32 v90, 16, v88
	v_lshrrev_b32_e32 v92, 16, v89
	v_lshrrev_b32_e32 v88, 16, v91
	ds_read_b64_tr_b16 v[202:203], v186 offset:27712
	ds_read_b64_tr_b16 v[204:205], v186 offset:30272
	ds_read_b64_tr_b16 v[206:207], v186 offset:27744
	ds_read_b64_tr_b16 v[208:209], v186 offset:30304
	v_cvt_pk_bf16_f32 v89, v85, v196
	v_and_or_b32 v88, v87, s11, v88
	v_and_or_b32 v87, v98, s11, v92
	v_and_or_b32 v86, v93, s11, v90
	ds_read_b64_tr_b16 v[90:91], v186 offset:32768
	ds_read_b64_tr_b16 v[92:93], v186 offset:35328
	ds_read_b64_tr_b16 v[236:237], v186 offset:32800
	ds_read_b64_tr_b16 v[238:239], v186 offset:35360
	ds_read_b64_tr_b16 v[246:247], v186 offset:32832
	ds_read_b64_tr_b16 v[248:249], v186 offset:35392
	ds_read_b64_tr_b16 v[210:211], v186 offset:32864
	ds_read_b64_tr_b16 v[212:213], v186 offset:35424
	s_waitcnt lgkmcnt(14)
	v_mfma_f32_16x16x32_bf16 v[150:153], v[150:153], v[94:97], 0
	v_mul_f32_e32 v63, 0x3fb8aa3b, v63
	v_exp_f32_e32 v78, v63
	v_sub_f32_e32 v63, v80, v60
	s_waitcnt lgkmcnt(6)
; #define LAS __attribute__((address_space(3)))
; __device__ __forceinline__ unsigned pk2(float lo, float hi) { return f2bf(lo) | (f2bf(hi) << 16); }
; #define MFMA16(a, b, c) __builtin_amdgcn_mfma_f32_16x16x32_bf16(a, b, c, 0, 0, 0)
; __device__ __forceinline__ v4i16_t vtr(const LAS unsigned char* p) { return __builtin_amdgcn_ds_read_tr16_b64_v4i16((LAS v4i16_t*)p); }
; __device__ __forceinline__ void attn_phase(const Params& p, LAS unsigned char* lds, const int bx, const int G, const int tid) {
;     ...
;             for (int e = 0; e < 4; ++e) { const float pv = __expf(st[j][e] - mx); st[j][e] = pv; sm += pv; }
;         sm += __shfl_xor(sm, 16); sm += __shfl_xor(sm, 32);
;         f32x4 ot[4];
; #pragma unroll
;         for (int dt = 0; dt < 4; ++dt) ot[dt] = (f32x4){0.f, 0.f, 0.f, 0.f};
; #pragma unroll
;         for (int ks = 0; ks < 5; ++ks) { v4u pw; pw.x = pk2(st[2 * ks][0], st[2 * ks][1]); pw.y = pk2(st[2 * ks][2], st[2 * ks][3]); pw.z = pk2(st[2 * ks + 1][0], st[2 * ks + 1][1]); pw.w = pk2(st[2 * ks + 1][2], st[2 * ks + 1][3]);
;             const bf16x8 pb = __builtin_bit_cast(bf16x8, pw);
; #pragma unroll
;             for (int dt = 0; dt < 4; ++dt) { const LAS unsigned char* vr = vbp + ks * 5120 + dt * 32;
;                 const v4i16_t lo = vtr(vr), hi = vtr(vr + 16 * 160);
;                 ot[dt] = MFMA16(__builtin_shufflevector(lo, hi, 0, 1, 2, 3, 4, 5, 6, 7), pb, ot[dt]); } }
	v_mfma_f32_16x16x32_bf16 v[90:93], v[90:93], v[86:89], v[150:153]
	s_nop 2
	ds_read_b64_tr_b16 v[214:215], v186 offset:37888
	ds_read_b64_tr_b16 v[216:217], v186 offset:40448
	v_mul_f32_e32 v63, 0x3fb8aa3b, v63
	v_exp_f32_e32 v80, v63
	v_mfma_f32_16x16x32_bf16 v[198:201], v[198:201], v[94:97], 0
	v_sub_f32_e32 v63, v82, v60
	v_mul_f32_e32 v63, 0x3fb8aa3b, v63
	v_exp_f32_e32 v82, v63
	s_waitcnt lgkmcnt(6)
	v_mfma_f32_16x16x32_bf16 v[150:153], v[236:239], v[86:89], v[198:201]
	s_nop 2
	ds_read_b64_tr_b16 v[218:219], v186 offset:37920
	ds_read_b64_tr_b16 v[220:221], v186 offset:40480
	v_sub_f32_e32 v63, v81, v60
	v_mul_f32_e32 v63, 0x3fb8aa3b, v63
	v_mfma_f32_16x16x32_bf16 v[202:205], v[202:205], v[94:97], 0
	v_exp_f32_e32 v81, v63
	v_sub_f32_e32 v63, v83, v60
	v_add_f32_e32 v62, v196, v62
	v_mul_f32_e32 v63, 0x3fb8aa3b, v63
	s_waitcnt lgkmcnt(6)
	v_mfma_f32_16x16x32_bf16 v[198:201], v[246:249], v[86:89], v[202:205]
	s_nop 2
	ds_read_b64_tr_b16 v[222:223], v186 offset:37952
	ds_read_b64_tr_b16 v[224:225], v186 offset:40512
	v_add_f32_e32 v62, v77, v62
	v_exp_f32_e32 v83, v63
	v_sub_f32_e32 v63, v76, v60
	v_mfma_f32_16x16x32_bf16 v[94:97], v[206:209], v[94:97], 0
	v_add_f32_e32 v62, v79, v62
	v_mul_f32_e32 v63, 0x3fb8aa3b, v63
	v_add_f32_e32 v62, v78, v62
	v_exp_f32_e32 v84, v63
	v_add_f32_e32 v62, v80, v62
	v_add_f32_e32 v62, v82, v62
	s_waitcnt lgkmcnt(6)
	v_mfma_f32_16x16x32_bf16 v[86:89], v[210:213], v[86:89], v[94:97]
	ds_read_b64_tr_b16 v[226:227], v186 offset:37984
	ds_read_b64_tr_b16 v[228:229], v186 offset:40544
	v_add_f32_e32 v62, v81, v62
	v_sub_f32_e32 v63, v188, v60
	v_add_f32_e32 v62, v83, v62
	v_bfe_u32 v94, v81, 16, 1
	v_bfe_u32 v95, v80, 16, 1
	v_bfe_u32 v96, v79, 16, 1
	v_add3_u32 v96, v79, v96, s33
	v_add3_u32 v79, v80, v95, s33
	v_add3_u32 v80, v81, v94, s33
	v_bfe_u32 v94, v82, 16, 1
	v_bfe_u32 v95, v83, 16, 1
	v_mul_f32_e32 v63, 0x3fb8aa3b, v63
	v_bfe_u32 v85, v84, 16, 1
	v_add3_u32 v83, v83, v95, s33
	v_add3_u32 v82, v82, v94, s33
	v_add_f32_e32 v62, v84, v62
	v_exp_f32_e32 v69, v63
	v_sub_f32_e32 v63, v187, v60
	v_add3_u32 v81, v84, v85, s33
	v_bfe_u32 v84, v77, 16, 1
	v_bfe_u32 v85, v78, 16, 1
	v_lshrrev_b32_e32 v82, 16, v82
	v_lshrrev_b32_e32 v83, 16, v83
	v_mul_f32_e32 v63, 0x3fb8aa3b, v63
	v_add3_u32 v78, v78, v85, s33
	v_add3_u32 v77, v77, v84, s33
	v_and_or_b32 v81, v81, s11, v83
	v_and_or_b32 v80, v80, s11, v82
	v_exp_f32_e32 v71, v63
	v_sub_f32_e32 v63, v73, v60
	v_mul_f32_e32 v63, 0x3fb8aa3b, v63
	v_exp_f32_e32 v70, v63
	v_sub_f32_e32 v63, v72, v60
	v_lshrrev_b32_e32 v77, 16, v77
	v_lshrrev_b32_e32 v78, 16, v78
	v_mul_f32_e32 v63, 0x3fb8aa3b, v63
	v_and_or_b32 v79, v79, s11, v78
	v_and_or_b32 v78, v96, s11, v77
	v_exp_f32_e32 v73, v63
	v_sub_f32_e32 v63, v75, v60
	s_waitcnt lgkmcnt(6)
	v_mfma_f32_16x16x32_bf16 v[82:85], v[214:217], v[78:81], v[90:93]
	s_nop 2
	v_mul_f32_e32 v63, 0x3fb8aa3b, v63
	v_exp_f32_e32 v72, v63
	v_sub_f32_e32 v63, v74, v60
	v_mul_f32_e32 v63, 0x3fb8aa3b, v63
	v_exp_f32_e32 v75, v63
	v_sub_f32_e32 v63, v190, v60
	v_mul_f32_e32 v63, 0x3fb8aa3b, v63
	s_waitcnt lgkmcnt(4)
	v_mfma_f32_16x16x32_bf16 v[90:93], v[218:221], v[78:81], v[150:153]
	s_nop 0
	v_add_f32_e32 v62, v69, v62
	v_exp_f32_e32 v74, v63
	v_sub_f32_e32 v63, v68, v60
	v_add_f32_e32 v62, v71, v62
	v_mul_f32_e32 v63, 0x3fb8aa3b, v63
	v_add_f32_e32 v62, v70, v62
	v_exp_f32_e32 v76, v63
	v_add_f32_e32 v62, v73, v62
	v_add_f32_e32 v62, v72, v62
	s_waitcnt lgkmcnt(2)
	v_mfma_f32_16x16x32_bf16 v[94:97], v[222:225], v[78:81], v[198:201]
	v_add_f32_e32 v62, v75, v62
	v_add_f32_e32 v62, v74, v62
	v_bfe_u32 v77, v76, 16, 1
	s_waitcnt lgkmcnt(0)
	v_mfma_f32_16x16x32_bf16 v[78:81], v[226:229], v[78:81], v[86:89]
	v_add_f32_e32 v62, v76, v62
	v_sub_f32_e32 v63, v192, v60
	v_mul_f32_e32 v63, 0x3fb8aa3b, v63
	v_bfe_u32 v87, v73, 16, 1
	v_bfe_u32 v88, v71, 16, 1
	v_add3_u32 v88, v71, v88, s33
	v_add3_u32 v71, v73, v87, s33
	v_bfe_u32 v87, v74, 16, 1
	v_add3_u32 v74, v74, v87, s33
	v_add3_u32 v73, v76, v77, s33
	v_bfe_u32 v76, v69, 16, 1
	v_bfe_u32 v77, v70, 16, 1
	v_lshrrev_b32_e32 v74, 16, v74
	v_add3_u32 v70, v70, v77, s33
	v_add3_u32 v69, v69, v76, s33
	v_and_or_b32 v73, v73, s11, v74
	v_cvt_pk_bf16_f32 v72, v72, v75
	ds_read_b64_tr_b16 v[74:75], v186 offset:43008
	ds_read_b64_tr_b16 v[76:77], v186 offset:45568
	v_lshrrev_b32_e32 v69, 16, v69
	v_lshrrev_b32_e32 v70, 16, v70
	v_and_or_b32 v71, v71, s11, v70
	v_and_or_b32 v70, v88, s11, v69
	v_exp_f32_e32 v66, v63
	v_sub_f32_e32 v63, v191, v60
	s_waitcnt lgkmcnt(0)
	v_mfma_f32_16x16x32_bf16 v[74:77], v[74:77], v[70:73], v[82:85]
	s_nop 2
	ds_read_b64_tr_b16 v[82:83], v186 offset:43040
	ds_read_b64_tr_b16 v[84:85], v186 offset:45600
	v_mul_f32_e32 v63, 0x3fb8aa3b, v63
	v_exp_f32_e32 v65, v63
	v_sub_f32_e32 v63, v195, v60
	v_mul_f32_e32 v63, 0x3fb8aa3b, v63
	v_exp_f32_e32 v67, v63
	v_sub_f32_e32 v63, v194, v60
	s_waitcnt lgkmcnt(0)
; #define LAS __attribute__((address_space(3)))
; __device__ __forceinline__ unsigned pk2(float lo, float hi) { return f2bf(lo) | (f2bf(hi) << 16); }
; #define MFMA16(a, b, c) __builtin_amdgcn_mfma_f32_16x16x32_bf16(a, b, c, 0, 0, 0)
; __device__ __forceinline__ v4i16_t vtr(const LAS unsigned char* p) { return __builtin_amdgcn_ds_read_tr16_b64_v4i16((LAS v4i16_t*)p); }
; __device__ __forceinline__ void attn_phase(const Params& p, LAS unsigned char* lds, const int bx, const int G, const int tid) {
;     ...
;         for (int ks = 0; ks < 5; ++ks) { v4u pw; pw.x = pk2(st[2 * ks][0], st[2 * ks][1]); pw.y = pk2(st[2 * ks][2], st[2 * ks][3]); pw.z = pk2(st[2 * ks + 1][0], st[2 * ks + 1][1]); pw.w = pk2(st[2 * ks + 1][2], st[2 * ks + 1][3]);
;             const bf16x8 pb = __builtin_bit_cast(bf16x8, pw);
; #pragma unroll
;             for (int dt = 0; dt < 4; ++dt) { const LAS unsigned char* vr = vbp + ks * 5120 + dt * 32;
;                 const v4i16_t lo = vtr(vr), hi = vtr(vr + 16 * 160);
;                 ot[dt] = MFMA16(__builtin_shufflevector(lo, hi, 0, 1, 2, 3, 4, 5, 6, 7), pb, ot[dt]); } }
;         { const size_t m = (size_t)(X.m0 + (X.nb * 64 + qi) * d + X.r); const float inv = 1.f / sm;
; #pragma unroll
;           for (int dt = 0; dt < 4; ++dt) { unsigned long long w = (unsigned long long)pk2(ot[dt][0] * inv, ot[dt][1] * inv) | ((unsigned long long)pk2(ot[dt][2] * inv, ot[dt][3] * inv) << 32);
	v_mfma_f32_16x16x32_bf16 v[82:85], v[82:85], v[70:73], v[90:93]
	ds_read_b64_tr_b16 v[86:87], v186 offset:43072
	ds_read_b64_tr_b16 v[88:89], v186 offset:45632
	s_nop 0
	ds_read_b64_tr_b16 v[90:91], v186 offset:43104
	ds_read_b64_tr_b16 v[92:93], v186 offset:45664
	v_mul_f32_e32 v63, 0x3fb8aa3b, v63
	v_exp_f32_e32 v68, v63
	v_add_f32_e32 v62, v66, v62
	v_add_f32_e32 v62, v65, v62
	v_add_f32_e32 v62, v67, v62
	s_waitcnt lgkmcnt(2)
	v_mfma_f32_16x16x32_bf16 v[86:89], v[86:89], v[70:73], v[94:97]
	v_add_f32_e32 v62, v68, v62
	ds_bpermute_b32 v63, v122, v62
	v_and_b32_sdwa v69, v67, v189 dst_sel:DWORD dst_unused:UNUSED_PAD src0_sel:WORD_1 src1_sel:DWORD
	s_waitcnt lgkmcnt(1)
	v_mfma_f32_16x16x32_bf16 v[70:73], v[90:93], v[70:73], v[78:81]
	v_add3_u32 v67, v67, v69, s33
	v_and_b32_sdwa v69, v68, v189 dst_sel:DWORD dst_unused:UNUSED_PAD src0_sel:WORD_1 src1_sel:DWORD
	v_add3_u32 v68, v68, v69, s33
	v_and_b32_sdwa v78, v66, v189 dst_sel:DWORD dst_unused:UNUSED_PAD src0_sel:WORD_1 src1_sel:DWORD
	v_add3_u32 v66, v66, v78, s33
	v_and_b32_sdwa v78, v65, v189 dst_sel:DWORD dst_unused:UNUSED_PAD src0_sel:WORD_1 src1_sel:DWORD
	v_add3_u32 v65, v65, v78, s33
	ds_read_b64_tr_b16 v[78:79], v186 offset:48128
	ds_read_b64_tr_b16 v[80:81], v186 offset:50688
	v_and_b32_e32 v68, 0xffff0000, v68
	v_and_b32_e32 v65, 0xffff0000, v65
	v_or_b32_sdwa v67, v68, v67 dst_sel:DWORD dst_unused:UNUSED_PAD src0_sel:DWORD src1_sel:WORD_1
	v_or_b32_sdwa v66, v65, v66 dst_sel:DWORD dst_unused:UNUSED_PAD src0_sel:DWORD src1_sel:WORD_1
	v_mov_b32_e32 v68, v0
	v_mov_b32_e32 v69, v0
	s_waitcnt lgkmcnt(2)
	v_add_f32_e32 v62, v62, v63
	ds_bpermute_b32 v63, v123, v62
	s_waitcnt lgkmcnt(1)
	v_mfma_f32_16x16x32_bf16 v[74:77], v[78:81], v[66:69], v[74:77]
	ds_read_b64_tr_b16 v[78:79], v186 offset:48160
	ds_read_b64_tr_b16 v[80:81], v186 offset:50720
	v_sub_u32_e32 v61, s13, v3
	s_cselect_b32 s12, s51, s37
	v_lshrrev_b32_e64 v61, v61, s50
	s_waitcnt lgkmcnt(0)
	v_mfma_f32_16x16x32_bf16 v[78:81], v[78:81], v[66:69], v[82:85]
	s_nop 2
	ds_read_b64_tr_b16 v[82:83], v186 offset:48192
	ds_read_b64_tr_b16 v[84:85], v186 offset:50752
	v_add_f32_e32 v62, v62, v63
	v_or_b32_e32 v63, v64, v121
	v_or_b32_e32 v61, s12, v61
	v_lshl_add_u32 v61, v63, v3, v61
	v_div_scale_f32 v3, s[12:13], v62, v62, 1.0
	v_rcp_f32_e32 v63, v3
	s_waitcnt lgkmcnt(0)
	v_mfma_f32_16x16x32_bf16 v[82:85], v[82:85], v[66:69], v[86:89]
	s_nop 2
	ds_read_b64_tr_b16 v[86:87], v186 offset:48224
	ds_read_b64_tr_b16 v[88:89], v186 offset:50784
	v_mov_b32_e32 v107, v0
	v_fma_f32 v64, -v3, v63, 1.0
	v_fmac_f32_e32 v63, v64, v63
	v_div_scale_f32 v64, vcc, 1.0, v62, 1.0
	v_mul_f32_e32 v65, v64, v63
	s_waitcnt lgkmcnt(0)
	v_mfma_f32_16x16x32_bf16 v[66:69], v[86:89], v[66:69], v[70:73]
	v_readlane_b32 s2, v254, 55
	v_readlane_b32 s3, v254, 56
	s_nop 0
	v_fma_f32 v70, -v3, v65, v64
	v_fmac_f32_e32 v65, v70, v63
	v_fma_f32 v3, -v3, v65, v64
	v_div_fmas_f32 v3, v3, v63, v65
	v_div_fixup_f32 v3, v3, v62, 1.0
	v_mov_b64_e32 v[64:65], s[90:91]
	v_lshlrev_b32_e32 v70, 6, v2
	v_mad_i64_i32 v[64:65], s[12:13], v61, s57, v[64:65]
	v_ashrrev_i32_e32 v71, 31, v70
	v_mul_f32_e32 v63, v3, v74
	v_lshl_add_u64 v[64:65], v[70:71], 1, v[64:65]
	v_mul_f32_e32 v70, v3, v75
	v_cvt_pk_bf16_f32 v70, v63, v70
	v_mul_f32_e32 v63, v3, v76
	v_mul_f32_e32 v71, v3, v77
	v_lshl_add_u64 v[64:65], v[64:65], 0, v[106:107]
	v_cvt_pk_bf16_f32 v71, v63, v71
	v_mul_f32_e32 v63, v3, v78
	global_store_dwordx2 v[64:65], v[70:71], off
	v_mul_f32_e32 v70, v3, v79
	v_cvt_pk_bf16_f32 v70, v63, v70
	v_mul_f32_e32 v63, v3, v80
	v_mul_f32_e32 v71, v3, v81
	v_cvt_pk_bf16_f32 v71, v63, v71
	v_mul_f32_e32 v63, v3, v82
	global_store_dwordx2 v[64:65], v[70:71], off offset:32
	v_mul_f32_e32 v70, v3, v83
	v_cvt_pk_bf16_f32 v70, v63, v70
	v_mul_f32_e32 v63, v3, v84
	v_mul_f32_e32 v71, v3, v85
	v_bfe_u32 v72, v71, 16, 1
	v_cvt_pk_bf16_f32 v71, v63, v71
	v_mul_f32_e32 v63, v3, v66
	v_mul_f32_e32 v66, v3, v67
	v_cvt_pk_bf16_f32 v66, v63, v66
	v_mul_f32_e32 v63, v3, v68
	v_mul_f32_e32 v3, v3, v69
	v_bfe_u32 v67, v63, 16, 1
	v_add3_u32 v63, v63, v67, s33
	v_bfe_u32 v67, v3, 16, 1
	v_lshrrev_b32_e32 v63, 16, v63
	v_add3_u32 v3, v3, v67, s33
	v_and_or_b32 v67, v3, s11, v63
	global_store_dwordx2 v[64:65], v[70:71], off offset:64
	global_store_dwordx2 v[64:65], v[66:67], off offset:96
	s_and_saveexec_b64 s[12:13], s[2:3]
	s_cbranch_execz .LBB0_386
	s_mov_b32 s37, 0x800000
	v_cmp_gt_f32_e32 vcc, s37, v62
	s_mov_b32 s37, 0x3f317217
	s_mov_b32 s2, 0x7f800000
	v_cndmask_b32_e64 v3, 0, 32, vcc
	v_ldexp_f32 v3, v62, v3
	v_log_f32_e32 v3, v3
	v_cndmask_b32_e32 v62, 0, v233, vcc
	v_mul_f32_e32 v63, 0x3f317217, v3
	v_fma_f32 v63, v3, s37, -v63
	v_fmac_f32_e32 v63, 0x3377d1cf, v3
	v_fmac_f32_e32 v63, 0x3f317217, v3
	v_cmp_lt_f32_e64 vcc, |v3|, s2
	v_readlane_b32 s2, v253, 7
	v_readlane_b32 s3, v253, 8
	v_cndmask_b32_e32 v3, v3, v63, vcc
	v_sub_f32_e32 v3, v3, v62
	v_add_f32_e32 v62, v60, v3
	v_ashrrev_i32_e32 v3, 31, v2
	v_mad_i64_i32 v[60:61], s[40:41], v61, 48, s[2:3]
	v_lshl_add_u64 v[2:3], v[2:3], 2, v[60:61]
	global_store_dword v[2:3], v62, off
	s_branch .LBB0_386
